# v14 + s_sleep between barrier polls replaced by s_nop (tighter polling)
# baseline (speedup 1.0000x reference)
.LBB0_71:
	s_and_b32 s10, s16, 0xff
	s_mov_b64 s[8:9], -1
	s_cmp_lg_u32 s10, 0
	s_mov_b64 s[12:13], -1
	s_nop 0
	s_cbranch_scc0 .LBB0_74
	s_and_b64 vcc, exec, s[12:13]
	s_cbranch_vccz .LBB0_70

.LBB0_89:
	s_and_b32 s10, s14, 0xff
	s_mov_b64 s[8:9], -1
	s_cmp_lg_u32 s10, 0
	s_mov_b64 s[12:13], -1
	s_nop 0
	s_cbranch_scc0 .LBB0_92
	s_and_b64 vcc, exec, s[12:13]
	s_cbranch_vccz .LBB0_88

.LBB0_104:
	s_and_b32 s14, s29, 0xff
	s_mov_b64 s[12:13], -1
	s_cmp_lg_u32 s14, 0
	s_mov_b64 s[16:17], -1
	s_nop 0
	s_cbranch_scc0 .LBB0_107
	s_and_b64 vcc, exec, s[16:17]
	s_cbranch_vccz .LBB0_103

.LBB0_148:
	s_and_b64 s[20:21], s[14:15], s[16:17]
	s_mov_b64 s[18:19], -1
	s_and_b64 vcc, exec, s[20:21]
	s_mov_b64 s[20:21], -1
	s_cbranch_vccnz .LBB0_138
	s_and_b32 s18, s24, 0xff
	s_cmp_eq_u32 s18, 0
	s_mov_b64 s[18:19], -1
	s_mov_b64 s[22:23], -1
	s_nop 0
	s_cbranch_scc1 .LBB0_152
	s_and_b64 vcc, exec, s[22:23]
	s_cbranch_vccz .LBB0_138

.LBB0_170:
	s_nop 0
	global_load_dword v3, v2, s[0:1] sc1
	s_and_b32 s10, s14, 0xff
	s_mov_b64 s[8:9], -1
	s_cmp_lg_u32 s10, 0
	s_mov_b64 s[12:13], -1
	s_cbranch_scc0 .LBB0_173
	s_and_b64 vcc, exec, s[12:13]
	s_cbranch_vccz .LBB0_169

.LBB0_184:
	s_and_b32 s8, s12, 0xff
	s_mov_b64 s[6:7], -1
	s_cmp_lg_u32 s8, 0
	s_mov_b64 s[10:11], -1
	s_nop 0
	s_cbranch_scc0 .LBB0_187
	s_and_b64 vcc, exec, s[10:11]
	s_cbranch_vccz .LBB0_183

.LBB0_203:
	s_and_b32 s12, s38, 0xff
	s_mov_b64 s[6:7], -1
	s_cmp_lg_u32 s12, 0
	s_mov_b64 s[14:15], -1
	s_nop 0
	s_cbranch_scc0 .LBB0_206
	s_and_b64 vcc, exec, s[14:15]
	s_cbranch_vccz .LBB0_202

.LBB0_249:
	global_load_dwordx4 v[210:213], v[220:221], off sc1
	s_waitcnt vmcnt(0)
	s_nop 0
	v_cmp_eq_u32_e32 vcc, 0, v210
	v_cmp_eq_u32_e64 s[8:9], 0, v211
	v_cmp_eq_u32_e64 s[10:11], 0, v212
	s_or_b64 s[8:9], vcc, s[8:9]
	s_or_b64 s[8:9], s[8:9], s[10:11]
	v_cmp_eq_u32_e32 vcc, 0, v213
	s_or_b64 s[10:11], s[8:9], vcc
	s_and_saveexec_b64 s[34:35], s[10:11]
	s_xor_b64 s[10:11], exec, s[34:35]
	s_cbranch_execz .LBB0_254
	s_memrealtime s[8:9]
	s_waitcnt lgkmcnt(0)
	s_sub_u32 s8, s8, s12
	s_subb_u32 s9, s9, s13
	v_cmp_gt_u64_e32 vcc, s[8:9], v[222:223]
	s_cbranch_vccnz .LBB0_252
	s_orn2_b64 s[26:27], s[24:25], exec
	s_nop 0
	s_mov_b64 s[8:9], -1
	s_branch .LBB0_253

.LBB0_331:
	s_and_b32 s12, s23, 0xff
	s_mov_b64 s[6:7], -1
	s_cmp_lg_u32 s12, 0
	s_mov_b64 s[14:15], -1
	s_nop 0
	s_cbranch_scc0 .LBB0_334
	s_and_b64 vcc, exec, s[14:15]
	s_cbranch_vccz .LBB0_330

.LBB0_428:
	s_and_b32 s6, s10, 0xff
	s_mov_b64 s[4:5], -1
	s_cmp_lg_u32 s6, 0
	s_mov_b64 s[8:9], -1
	s_nop 0
	s_cbranch_scc0 .LBB0_431
	s_and_b64 vcc, exec, s[8:9]
	s_cbranch_vccz .LBB0_427

.LBB0_443:
	s_and_b32 s6, s14, 0xff
	s_mov_b64 s[4:5], -1
	s_cmp_lg_u32 s6, 0
	s_mov_b64 s[12:13], -1
	s_nop 0
	s_cbranch_scc0 .LBB0_446
	s_and_b64 vcc, exec, s[12:13]
	s_cbranch_vccz .LBB0_442

.LBB0_497:
	global_load_dwordx4 v[146:149], v[218:219], off sc1
	s_waitcnt vmcnt(0)
	s_nop 0
	v_cmp_eq_u32_e32 vcc, 0, v146
	v_cmp_eq_u32_e64 s[8:9], 0, v147
	v_cmp_eq_u32_e64 s[10:11], 0, v148
	s_or_b64 s[8:9], vcc, s[8:9]
	s_or_b64 s[8:9], s[8:9], s[10:11]
	v_cmp_eq_u32_e32 vcc, 0, v149
	s_or_b64 s[10:11], s[8:9], vcc
	s_and_saveexec_b64 s[36:37], s[10:11]
	s_xor_b64 s[10:11], exec, s[36:37]
	s_cbranch_execz .LBB0_502
	s_memrealtime s[8:9]
	s_waitcnt lgkmcnt(0)
	s_sub_u32 s8, s8, s14
	s_subb_u32 s9, s9, s15
	v_cmp_gt_u64_e32 vcc, s[8:9], v[220:221]
	s_cbranch_vccnz .LBB0_500
	s_orn2_b64 s[28:29], s[26:27], exec
	s_nop 0
	s_mov_b64 s[8:9], -1
	s_branch .LBB0_501

.LBB0_595:
	s_and_b32 s8, s16, 0xff
	s_mov_b64 s[6:7], -1
	s_cmp_lg_u32 s8, 0
	s_mov_b64 s[10:11], -1
	s_nop 0
	s_cbranch_scc0 .LBB0_598
	s_and_b64 vcc, exec, s[10:11]
	s_cbranch_vccz .LBB0_594

.LBB0_923:
	s_and_b32 s6, s31, 0xff
	s_mov_b64 s[4:5], -1
	s_cmp_lg_u32 s6, 0
	s_mov_b64 s[12:13], -1
	s_nop 0
	s_cbranch_scc0 .LBB0_926
	s_and_b64 vcc, exec, s[12:13]
	s_cbranch_vccz .LBB0_922

.LBB0_969:
	global_load_dwordx4 v[18:21], v[148:149], off sc1
	s_waitcnt vmcnt(0)
	s_nop 0
	v_cmp_eq_u32_e32 vcc, 0, v18
	v_cmp_eq_u32_e64 s[8:9], 0, v19
	v_cmp_eq_u32_e64 s[10:11], 0, v20
	s_or_b64 s[8:9], vcc, s[8:9]
	s_or_b64 s[8:9], s[8:9], s[10:11]
	v_cmp_eq_u32_e32 vcc, 0, v21
	s_or_b64 s[10:11], s[8:9], vcc
	s_and_saveexec_b64 s[36:37], s[10:11]
	s_xor_b64 s[10:11], exec, s[36:37]
	s_cbranch_execz .LBB0_974
	s_memrealtime s[8:9]
	s_waitcnt lgkmcnt(0)
	s_sub_u32 s8, s8, s14
	s_subb_u32 s9, s9, s15
	v_cmp_gt_u64_e32 vcc, s[8:9], v[150:151]
	s_cbranch_vccnz .LBB0_972
	s_orn2_b64 s[28:29], s[26:27], exec
	s_nop 0
	s_mov_b64 s[8:9], -1
	s_branch .LBB0_973

.LBB0_1055:
	s_and_b32 s14, s31, 0xff
	s_mov_b64 s[12:13], -1
	s_cmp_lg_u32 s14, 0
	s_mov_b64 s[16:17], -1
	s_nop 0
	s_cbranch_scc0 .LBB0_1058
	s_and_b64 vcc, exec, s[16:17]
	s_cbranch_vccz .LBB0_1054

.LBB0_1095:
	s_and_b32 s12, s16, 0xff
	s_mov_b64 s[4:5], -1
	s_cmp_lg_u32 s12, 0
	s_mov_b64 s[14:15], -1
	s_nop 0
	s_cbranch_scc0 .LBB0_1098
	s_and_b64 vcc, exec, s[14:15]
	s_cbranch_vccz .LBB0_1094

.LBB0_1106:
	s_and_b32 s16, s24, 0xff
	s_mov_b64 s[4:5], -1
	s_cmp_lg_u32 s16, 0
	s_mov_b64 s[18:19], -1
	s_nop 0
	s_cbranch_scc0 .LBB0_1109
	s_and_b64 vcc, exec, s[18:19]
	s_cbranch_vccz .LBB0_1105

.LBB0_1165:
	global_load_dwordx4 v[146:149], v[216:217], off sc1
	s_waitcnt vmcnt(0)
	s_nop 0
	v_cmp_eq_u32_e32 vcc, 0, v146
	v_cmp_eq_u32_e64 s[0:1], 0, v147
	v_cmp_eq_u32_e64 s[2:3], 0, v148
	s_or_b64 s[0:1], vcc, s[0:1]
	s_or_b64 s[0:1], s[0:1], s[2:3]
	v_cmp_eq_u32_e32 vcc, 0, v149
	s_or_b64 s[2:3], s[0:1], vcc
	s_and_saveexec_b64 s[28:29], s[2:3]
	s_xor_b64 s[2:3], exec, s[28:29]
	s_cbranch_execz .LBB0_1170
	s_memrealtime s[0:1]
	s_waitcnt lgkmcnt(0)
	s_sub_u32 s0, s0, s14
	s_subb_u32 s1, s1, s15
	v_cmp_gt_u64_e32 vcc, s[0:1], v[218:219]
	s_cbranch_vccnz .LBB0_1168
	s_orn2_b64 s[22:23], s[20:21], exec
	s_nop 0
	s_mov_b64 s[0:1], -1
	s_branch .LBB0_1169
